# FF1 K-loop: the four loop-invariant LDS fragment base addresses kept in spare VGPRs, removing the VALU adds at the head of two load segments per iteration
# speedup vs baseline: 1.0259x; 1.0077x over previous
.LBB0_28:
	s_ashr_i32 s47, s46, 31
	s_lshl_b64 s[6:7], s[46:47], 19
	s_add_u32 s48, s50, s6
	s_addc_u32 s49, s34, s7
	s_and_b64 s[6:7], s[42:43], exec
	s_cselect_b32 s5, s49, s1
	s_cselect_b32 s6, s48, s0
	s_ashr_i32 s45, s44, 31
	s_lshl_b64 s[8:9], s[44:45], 19
	s_add_u32 s54, s16, s8
	s_addc_u32 s55, s17, s9
	s_and_b64 s[8:9], s[42:43], exec
	s_cselect_b32 s7, s55, s29
	s_cselect_b32 s8, s54, s28
	s_add_u32 s0, s0, 0x40080
	s_addc_u32 s1, s1, 0
	s_add_u32 s9, s28, 0x100
	v_mov_b32_e32 v0, 0
	s_addc_u32 s10, s29, 0
	s_mov_b32 s11, -2
	v_mov_b32_e32 v1, v0
	v_mov_b32_e32 v2, v0
	v_mov_b32_e32 v3, v0
	v_mov_b32_e32 v4, v0
	v_mov_b32_e32 v5, v0
	v_mov_b32_e32 v6, v0
	v_mov_b32_e32 v7, v0
	v_mov_b32_e32 v16, v0
	v_mov_b32_e32 v17, v0
	v_mov_b32_e32 v18, v0
	v_mov_b32_e32 v19, v0
	v_mov_b32_e32 v20, v0
	v_mov_b32_e32 v21, v0
	v_mov_b32_e32 v22, v0
	v_mov_b32_e32 v23, v0
	s_waitcnt vmcnt(0)
	v_mov_b32_e32 v32, v0
	v_mov_b32_e32 v33, v0
	v_mov_b32_e32 v34, v0
	v_mov_b32_e32 v35, v0
	v_mov_b32_e32 v36, v0
	v_mov_b32_e32 v37, v0
	v_mov_b32_e32 v38, v0
	v_mov_b32_e32 v39, v0
	v_mov_b32_e32 v48, v0
	v_mov_b32_e32 v49, v0
	v_mov_b32_e32 v50, v0
	v_mov_b32_e32 v51, v0
	v_mov_b32_e32 v52, v0
	v_mov_b32_e32 v53, v0
	v_mov_b32_e32 v54, v0
	v_mov_b32_e32 v55, v0
	v_mov_b32_e32 v8, v0
	v_mov_b32_e32 v9, v0
	v_mov_b32_e32 v10, v0
	v_mov_b32_e32 v11, v0
	v_mov_b32_e32 v12, v0
	v_mov_b32_e32 v13, v0
	v_mov_b32_e32 v14, v0
	v_mov_b32_e32 v15, v0
	v_mov_b32_e32 v24, v0
	v_mov_b32_e32 v25, v0
	v_mov_b32_e32 v26, v0
	v_mov_b32_e32 v27, v0
	v_mov_b32_e32 v28, v0
	v_mov_b32_e32 v29, v0
	v_mov_b32_e32 v30, v0
	v_mov_b32_e32 v31, v0
	v_mov_b32_e32 v40, v0
	v_mov_b32_e32 v41, v0
	v_mov_b32_e32 v42, v0
	v_mov_b32_e32 v43, v0
	v_mov_b32_e32 v44, v0
	v_mov_b32_e32 v45, v0
	v_mov_b32_e32 v46, v0
	v_mov_b32_e32 v47, v0
	v_mov_b32_e32 v56, v0
	v_mov_b32_e32 v57, v0
	v_mov_b32_e32 v58, v0
	v_mov_b32_e32 v59, v0
	v_mov_b32_e32 v60, v0
	v_mov_b32_e32 v61, v0
	v_mov_b32_e32 v62, v0
	v_mov_b32_e32 v63, v0
	v_mov_b32_e32 v66, v0
	v_mov_b32_e32 v67, v0
	v_mov_b32_e32 v68, v0
	v_mov_b32_e32 v69, v0
	v_mov_b32_e32 v70, v0
	v_mov_b32_e32 v71, v0
	v_mov_b32_e32 v72, v0
	v_mov_b32_e32 v73, v0
	v_mov_b32_e32 v82, v0
	v_mov_b32_e32 v83, v0
	v_mov_b32_e32 v84, v0
	v_mov_b32_e32 v85, v0
	v_mov_b32_e32 v86, v0
	v_mov_b32_e32 v87, v0
	v_mov_b32_e32 v88, v0
	v_mov_b32_e32 v89, v0
	v_mov_b32_e32 v98, v0
	v_mov_b32_e32 v99, v0
	v_mov_b32_e32 v100, v0
	v_mov_b32_e32 v101, v0
	v_mov_b32_e32 v102, v0
	v_mov_b32_e32 v103, v0
	v_mov_b32_e32 v104, v0
	v_mov_b32_e32 v105, v0
	v_mov_b32_e32 v114, v0
	v_mov_b32_e32 v115, v0
	v_mov_b32_e32 v116, v0
	v_mov_b32_e32 v117, v0
	v_mov_b32_e32 v118, v0
	v_mov_b32_e32 v119, v0
	v_mov_b32_e32 v120, v0
	v_mov_b32_e32 v121, v0
	v_mov_b32_e32 v74, v0
	v_mov_b32_e32 v75, v0
	v_mov_b32_e32 v76, v0
	v_mov_b32_e32 v77, v0
	v_mov_b32_e32 v78, v0
	v_mov_b32_e32 v79, v0
	v_mov_b32_e32 v80, v0
	v_mov_b32_e32 v81, v0
	v_mov_b32_e32 v90, v0
	v_mov_b32_e32 v91, v0
	v_mov_b32_e32 v92, v0
	v_mov_b32_e32 v93, v0
	v_mov_b32_e32 v94, v0
	v_mov_b32_e32 v95, v0
	v_mov_b32_e32 v96, v0
	v_mov_b32_e32 v97, v0
	v_mov_b32_e32 v106, v0
	v_mov_b32_e32 v107, v0
	v_mov_b32_e32 v108, v0
	v_mov_b32_e32 v109, v0
	v_mov_b32_e32 v110, v0
	v_mov_b32_e32 v111, v0
	v_mov_b32_e32 v112, v0
	v_mov_b32_e32 v113, v0
	v_mov_b32_e32 v122, v0
	v_mov_b32_e32 v123, v0
	v_mov_b32_e32 v124, v0
	v_mov_b32_e32 v125, v0
	v_mov_b32_e32 v126, v0
	v_mov_b32_e32 v127, v0
	v_mov_b32_e32 v128, v0
	v_mov_b32_e32 v129, v0
	s_mov_b64 s[40:41], 0x80
	v_add_u32_e32 v244, 0x10000, v179
	v_add_u32_e32 v245, 0x14000, v179
	v_add_u32_e32 v247, 0x18000, v179
	v_add_u32_e32 v248, 0x1c000, v179
.LBB0_29:
	s_add_u32 s12, s0, 0xfffc0080
	s_addc_u32 s13, s1, -1
	s_add_i32 s14, 0, 0x10000
	s_cmp_eq_u32 s11, 12
	s_cselect_b32 s37, s5, s13
	s_cselect_b32 s36, s6, s12
	s_cselect_b32 s29, s7, s10
	s_cselect_b32 s28, s8, s9
	s_add_i32 s15, 0, 0x14000
	ds_read_b128 v[130:133], v244
	ds_read_b128 v[134:137], v244 offset:1024
	ds_read_b128 v[138:141], v244 offset:2048
	ds_read_b128 v[142:145], v244 offset:3072
	ds_read_b128 v[146:149], v245
	ds_read_b128 v[160:163], v245 offset:1024
	ds_read_b128 v[164:167], v245 offset:2048
	ds_read_b128 v[168:171], v245 offset:3072
	s_mov_b32 m0, s80
	v_lshl_add_u64 v[208:209], s[0:1], 0, v[156:157]
	ds_read_b128 v[172:175], v182
	ds_read_b128 v[184:187], v182 offset:1024
	ds_read_b128 v[188:191], v182 offset:2048
	ds_read_b128 v[192:195], v182 offset:3072
	ds_read_b128 v[196:199], v182 offset:4096
	ds_read_b128 v[200:203], v182 offset:5120
	ds_read_b128 v[204:207], v182 offset:6144
	ds_read_b128 v[226:229], v182 offset:7168
	global_load_lds_dwordx4 v[208:209], off
	v_lshl_add_u64 v[208:209], s[0:1], 0, v[158:159]
	s_add_i32 m0, s25, 0xe000
	s_nop 0
	global_load_lds_dwordx4 v[208:209], off
	s_waitcnt vmcnt(8)
	s_waitcnt lgkmcnt(0)
	s_barrier
	s_setprio 1
	s_waitcnt lgkmcnt(0)
	v_mfma_f32_16x16x32_bf16 v[126:129], v[130:133], v[172:175], v[126:129]
	v_mfma_f32_16x16x32_bf16 v[122:125], v[138:141], v[172:175], v[122:125]
	v_mfma_f32_16x16x32_bf16 v[110:113], v[130:133], v[188:191], v[110:113]
	v_mfma_f32_16x16x32_bf16 v[106:109], v[138:141], v[188:191], v[106:109]
	v_mfma_f32_16x16x32_bf16 v[94:97], v[130:133], v[196:199], v[94:97]
	v_mfma_f32_16x16x32_bf16 v[90:93], v[138:141], v[196:199], v[90:93]
	v_mfma_f32_16x16x32_bf16 v[78:81], v[130:133], v[204:207], v[78:81]
	v_mfma_f32_16x16x32_bf16 v[74:77], v[138:141], v[204:207], v[74:77]
	v_mfma_f32_16x16x32_bf16 v[126:129], v[134:137], v[184:187], v[126:129]
	v_mfma_f32_16x16x32_bf16 v[122:125], v[142:145], v[184:187], v[122:125]
	v_mfma_f32_16x16x32_bf16 v[110:113], v[134:137], v[192:195], v[110:113]
	v_mfma_f32_16x16x32_bf16 v[106:109], v[142:145], v[192:195], v[106:109]
	v_mfma_f32_16x16x32_bf16 v[94:97], v[134:137], v[200:203], v[94:97]
	v_mfma_f32_16x16x32_bf16 v[90:93], v[142:145], v[200:203], v[90:93]
	v_mfma_f32_16x16x32_bf16 v[78:81], v[134:137], v[226:229], v[78:81]
	v_mfma_f32_16x16x32_bf16 v[74:77], v[142:145], v[226:229], v[74:77]
	s_setprio 0
	s_setprio 1
	v_mfma_f32_16x16x32_bf16 v[118:121], v[146:149], v[172:175], v[118:121]
	v_mfma_f32_16x16x32_bf16 v[114:117], v[164:167], v[172:175], v[114:117]
	v_mfma_f32_16x16x32_bf16 v[102:105], v[146:149], v[188:191], v[102:105]
	v_mfma_f32_16x16x32_bf16 v[98:101], v[164:167], v[188:191], v[98:101]
	v_mfma_f32_16x16x32_bf16 v[86:89], v[146:149], v[196:199], v[86:89]
	v_mfma_f32_16x16x32_bf16 v[82:85], v[164:167], v[196:199], v[82:85]
	v_mfma_f32_16x16x32_bf16 v[70:73], v[146:149], v[204:207], v[70:73]
	v_mfma_f32_16x16x32_bf16 v[66:69], v[164:167], v[204:207], v[66:69]
	v_mfma_f32_16x16x32_bf16 v[118:121], v[160:163], v[184:187], v[118:121]
	v_mfma_f32_16x16x32_bf16 v[114:117], v[168:171], v[184:187], v[114:117]
	v_mfma_f32_16x16x32_bf16 v[102:105], v[160:163], v[192:195], v[102:105]
	v_mfma_f32_16x16x32_bf16 v[98:101], v[168:171], v[192:195], v[98:101]
	v_mfma_f32_16x16x32_bf16 v[86:89], v[160:163], v[200:203], v[86:89]
	v_mfma_f32_16x16x32_bf16 v[82:85], v[168:171], v[200:203], v[82:85]
	v_mfma_f32_16x16x32_bf16 v[70:73], v[160:163], v[226:229], v[70:73]
	v_mfma_f32_16x16x32_bf16 v[66:69], v[168:171], v[226:229], v[66:69]
	s_setprio 0
	s_barrier
	s_add_i32 s12, s14, s38
	v_lshl_add_u64 v[208:209], s[28:29], 0, v[64:65]
	s_mov_b32 m0, s12
	ds_read_b128 v[172:175], v182 offset:16384
	ds_read_b128 v[184:187], v182 offset:17408
	ds_read_b128 v[188:191], v182 offset:18432
	ds_read_b128 v[192:195], v182 offset:19456
	ds_read_b128 v[196:199], v182 offset:20480
	ds_read_b128 v[200:203], v182 offset:21504
	ds_read_b128 v[204:207], v182 offset:22528
	ds_read_b128 v[226:229], v182 offset:23552
	global_load_lds_dwordx4 v[208:209], off
	s_add_i32 m0, s12, 0x2000
	s_add_u32 s12, s28, 0x40000
	v_lshl_add_u64 v[210:211], s[28:29], 0, v[150:151]
	s_addc_u32 s13, s29, 0
	s_add_i32 s14, s15, s38
	global_load_lds_dwordx4 v[210:211], off
	v_lshl_add_u64 v[212:213], s[12:13], 0, v[64:65]
	s_mov_b32 m0, s14
	v_lshl_add_u64 v[218:219], s[36:37], 0, v[152:153]
	global_load_lds_dwordx4 v[212:213], off
	v_lshl_add_u64 v[212:213], s[12:13], 0, v[150:151]
	s_add_i32 m0, s14, 0x2000
	v_readlane_b32 s12, v251, 21
	global_load_lds_dwordx4 v[212:213], off
	v_lshl_add_u64 v[212:213], s[36:37], 0, v[154:155]
	s_mov_b32 m0, s25
	s_nop 0
	global_load_lds_dwordx4 v[212:213], off
	s_mov_b32 m0, s12
	s_nop 0
	global_load_lds_dwordx4 v[218:219], off
	s_waitcnt vmcnt(8)
	s_waitcnt lgkmcnt(0)
	s_barrier
	s_setprio 1
	s_waitcnt lgkmcnt(0)
	v_mfma_f32_16x16x32_bf16 v[60:63], v[130:133], v[172:175], v[60:63]
	v_mfma_f32_16x16x32_bf16 v[56:59], v[138:141], v[172:175], v[56:59]
	v_mfma_f32_16x16x32_bf16 v[44:47], v[130:133], v[188:191], v[44:47]
	v_mfma_f32_16x16x32_bf16 v[40:43], v[138:141], v[188:191], v[40:43]
	v_mfma_f32_16x16x32_bf16 v[28:31], v[130:133], v[196:199], v[28:31]
	v_mfma_f32_16x16x32_bf16 v[24:27], v[138:141], v[196:199], v[24:27]
	v_mfma_f32_16x16x32_bf16 v[12:15], v[130:133], v[204:207], v[12:15]
	v_mfma_f32_16x16x32_bf16 v[8:11], v[138:141], v[204:207], v[8:11]
	v_mfma_f32_16x16x32_bf16 v[60:63], v[134:137], v[184:187], v[60:63]
	v_mfma_f32_16x16x32_bf16 v[56:59], v[142:145], v[184:187], v[56:59]
	v_mfma_f32_16x16x32_bf16 v[44:47], v[134:137], v[192:195], v[44:47]
	v_mfma_f32_16x16x32_bf16 v[40:43], v[142:145], v[192:195], v[40:43]
	v_mfma_f32_16x16x32_bf16 v[28:31], v[134:137], v[200:203], v[28:31]
	v_mfma_f32_16x16x32_bf16 v[24:27], v[142:145], v[200:203], v[24:27]
	v_mfma_f32_16x16x32_bf16 v[12:15], v[134:137], v[226:229], v[12:15]
	v_mfma_f32_16x16x32_bf16 v[8:11], v[142:145], v[226:229], v[8:11]
	s_setprio 0
	s_setprio 1
	v_mfma_f32_16x16x32_bf16 v[52:55], v[146:149], v[172:175], v[52:55]
	v_mfma_f32_16x16x32_bf16 v[48:51], v[164:167], v[172:175], v[48:51]
	v_mfma_f32_16x16x32_bf16 v[36:39], v[146:149], v[188:191], v[36:39]
	v_mfma_f32_16x16x32_bf16 v[32:35], v[164:167], v[188:191], v[32:35]
	v_mfma_f32_16x16x32_bf16 v[20:23], v[146:149], v[196:199], v[20:23]
	v_mfma_f32_16x16x32_bf16 v[16:19], v[164:167], v[196:199], v[16:19]
	v_mfma_f32_16x16x32_bf16 v[4:7], v[146:149], v[204:207], v[4:7]
	v_mfma_f32_16x16x32_bf16 v[0:3], v[164:167], v[204:207], v[0:3]
	v_mfma_f32_16x16x32_bf16 v[52:55], v[160:163], v[184:187], v[52:55]
	v_mfma_f32_16x16x32_bf16 v[48:51], v[168:171], v[184:187], v[48:51]
	v_mfma_f32_16x16x32_bf16 v[36:39], v[160:163], v[192:195], v[36:39]
	v_mfma_f32_16x16x32_bf16 v[32:35], v[168:171], v[192:195], v[32:35]
	v_mfma_f32_16x16x32_bf16 v[20:23], v[160:163], v[200:203], v[20:23]
	v_mfma_f32_16x16x32_bf16 v[16:19], v[168:171], v[200:203], v[16:19]
	v_mfma_f32_16x16x32_bf16 v[4:7], v[160:163], v[226:229], v[4:7]
	v_mfma_f32_16x16x32_bf16 v[0:3], v[168:171], v[226:229], v[0:3]
	s_setprio 0
	s_barrier
	s_add_i32 s14, 0, 0x18000
	s_add_i32 s15, 0, 0x1c000
	ds_read_b128 v[130:133], v247
	ds_read_b128 v[134:137], v247 offset:1024
	ds_read_b128 v[138:141], v247 offset:2048
	ds_read_b128 v[142:145], v247 offset:3072
	ds_read_b128 v[146:149], v248
	ds_read_b128 v[160:163], v248 offset:1024
	ds_read_b128 v[164:167], v248 offset:2048
	ds_read_b128 v[168:171], v248 offset:3072
	s_add_u32 s12, s36, 0x40000
	s_addc_u32 s13, s37, 0
	s_mov_b32 m0, s75
	v_lshl_add_u64 v[230:231], s[12:13], 0, v[154:155]
	ds_read_b128 v[172:175], v182 offset:32768
	ds_read_b128 v[184:187], v182 offset:33792
	ds_read_b128 v[188:191], v182 offset:34816
	ds_read_b128 v[192:195], v182 offset:35840
	ds_read_b128 v[196:199], v182 offset:36864
	ds_read_b128 v[200:203], v182 offset:37888
	ds_read_b128 v[204:207], v182 offset:38912
	ds_read_b128 v[226:229], v182 offset:39936
	global_load_lds_dwordx4 v[230:231], off
	v_lshl_add_u64 v[230:231], s[12:13], 0, v[152:153]
	s_mov_b32 m0, s74
	s_nop 0
	global_load_lds_dwordx4 v[230:231], off
	s_waitcnt vmcnt(8)
	s_waitcnt lgkmcnt(0)
	s_barrier
	s_setprio 1
	s_waitcnt lgkmcnt(0)
	v_mfma_f32_16x16x32_bf16 v[126:129], v[130:133], v[172:175], v[126:129]
	v_mfma_f32_16x16x32_bf16 v[122:125], v[138:141], v[172:175], v[122:125]
	v_mfma_f32_16x16x32_bf16 v[110:113], v[130:133], v[188:191], v[110:113]
	v_mfma_f32_16x16x32_bf16 v[106:109], v[138:141], v[188:191], v[106:109]
	v_mfma_f32_16x16x32_bf16 v[94:97], v[130:133], v[196:199], v[94:97]
	v_mfma_f32_16x16x32_bf16 v[90:93], v[138:141], v[196:199], v[90:93]
	v_mfma_f32_16x16x32_bf16 v[78:81], v[130:133], v[204:207], v[78:81]
	v_mfma_f32_16x16x32_bf16 v[74:77], v[138:141], v[204:207], v[74:77]
	v_mfma_f32_16x16x32_bf16 v[126:129], v[134:137], v[184:187], v[126:129]
	v_mfma_f32_16x16x32_bf16 v[122:125], v[142:145], v[184:187], v[122:125]
	v_mfma_f32_16x16x32_bf16 v[110:113], v[134:137], v[192:195], v[110:113]
	v_mfma_f32_16x16x32_bf16 v[106:109], v[142:145], v[192:195], v[106:109]
	v_mfma_f32_16x16x32_bf16 v[94:97], v[134:137], v[200:203], v[94:97]
	v_mfma_f32_16x16x32_bf16 v[90:93], v[142:145], v[200:203], v[90:93]
	v_mfma_f32_16x16x32_bf16 v[78:81], v[134:137], v[226:229], v[78:81]
	v_mfma_f32_16x16x32_bf16 v[74:77], v[142:145], v[226:229], v[74:77]
	s_setprio 0
	s_setprio 1
	v_mfma_f32_16x16x32_bf16 v[118:121], v[146:149], v[172:175], v[118:121]
	v_mfma_f32_16x16x32_bf16 v[114:117], v[164:167], v[172:175], v[114:117]
	v_mfma_f32_16x16x32_bf16 v[102:105], v[146:149], v[188:191], v[102:105]
	v_mfma_f32_16x16x32_bf16 v[98:101], v[164:167], v[188:191], v[98:101]
	v_mfma_f32_16x16x32_bf16 v[86:89], v[146:149], v[196:199], v[86:89]
	v_mfma_f32_16x16x32_bf16 v[82:85], v[164:167], v[196:199], v[82:85]
	v_mfma_f32_16x16x32_bf16 v[70:73], v[146:149], v[204:207], v[70:73]
	v_mfma_f32_16x16x32_bf16 v[66:69], v[164:167], v[204:207], v[66:69]
	v_mfma_f32_16x16x32_bf16 v[118:121], v[160:163], v[184:187], v[118:121]
	v_mfma_f32_16x16x32_bf16 v[114:117], v[168:171], v[184:187], v[114:117]
	v_mfma_f32_16x16x32_bf16 v[102:105], v[160:163], v[192:195], v[102:105]
	v_mfma_f32_16x16x32_bf16 v[98:101], v[168:171], v[192:195], v[98:101]
	v_mfma_f32_16x16x32_bf16 v[86:89], v[160:163], v[200:203], v[86:89]
	v_mfma_f32_16x16x32_bf16 v[82:85], v[168:171], v[200:203], v[82:85]
	v_mfma_f32_16x16x32_bf16 v[70:73], v[160:163], v[226:229], v[70:73]
	v_mfma_f32_16x16x32_bf16 v[66:69], v[168:171], v[226:229], v[66:69]
	s_setprio 0
	s_barrier
	s_add_i32 s12, s14, s38
	v_lshl_add_u64 v[208:209], v[208:209], 0, s[40:41]
	s_mov_b32 m0, s12
	ds_read_b128 v[172:175], v182 offset:49152
	ds_read_b128 v[184:187], v182 offset:50176
	ds_read_b128 v[188:191], v182 offset:51200
	ds_read_b128 v[192:195], v182 offset:52224
	ds_read_b128 v[196:199], v182 offset:53248
	ds_read_b128 v[200:203], v182 offset:54272
	ds_read_b128 v[204:207], v182 offset:55296
	ds_read_b128 v[226:229], v182 offset:56320
	global_load_lds_dwordx4 v[208:209], off
	s_add_i32 m0, s12, 0x2000
	s_add_u32 s12, s28, 0x40080
	v_lshl_add_u64 v[208:209], v[210:211], 0, s[40:41]
	s_addc_u32 s13, s29, 0
	s_add_i32 s14, s15, s38
	global_load_lds_dwordx4 v[208:209], off
	v_lshl_add_u64 v[208:209], s[12:13], 0, v[64:65]
	s_mov_b32 m0, s14
	s_nop 0
	global_load_lds_dwordx4 v[208:209], off
	v_lshl_add_u64 v[208:209], s[12:13], 0, v[150:151]
	s_add_i32 m0, s14, 0x2000
	s_nop 0
	global_load_lds_dwordx4 v[208:209], off
	v_lshl_add_u64 v[208:209], v[212:213], 0, s[40:41]
	s_mov_b32 m0, s92
	s_nop 0
	global_load_lds_dwordx4 v[208:209], off
	v_lshl_add_u64 v[208:209], v[218:219], 0, s[40:41]
	s_mov_b32 m0, s78
	s_nop 0
	global_load_lds_dwordx4 v[208:209], off
	s_waitcnt vmcnt(8)
	s_waitcnt lgkmcnt(0)
	s_barrier
	s_setprio 1
	s_waitcnt lgkmcnt(0)
	v_mfma_f32_16x16x32_bf16 v[60:63], v[130:133], v[172:175], v[60:63]
	v_mfma_f32_16x16x32_bf16 v[56:59], v[138:141], v[172:175], v[56:59]
	v_mfma_f32_16x16x32_bf16 v[44:47], v[130:133], v[188:191], v[44:47]
	v_mfma_f32_16x16x32_bf16 v[40:43], v[138:141], v[188:191], v[40:43]
	v_mfma_f32_16x16x32_bf16 v[28:31], v[130:133], v[196:199], v[28:31]
	v_mfma_f32_16x16x32_bf16 v[24:27], v[138:141], v[196:199], v[24:27]
	v_mfma_f32_16x16x32_bf16 v[12:15], v[130:133], v[204:207], v[12:15]
	v_mfma_f32_16x16x32_bf16 v[8:11], v[138:141], v[204:207], v[8:11]
	v_mfma_f32_16x16x32_bf16 v[60:63], v[134:137], v[184:187], v[60:63]
	v_mfma_f32_16x16x32_bf16 v[56:59], v[142:145], v[184:187], v[56:59]
	v_mfma_f32_16x16x32_bf16 v[44:47], v[134:137], v[192:195], v[44:47]
	v_mfma_f32_16x16x32_bf16 v[40:43], v[142:145], v[192:195], v[40:43]
	v_mfma_f32_16x16x32_bf16 v[28:31], v[134:137], v[200:203], v[28:31]
	v_mfma_f32_16x16x32_bf16 v[24:27], v[142:145], v[200:203], v[24:27]
	v_mfma_f32_16x16x32_bf16 v[12:15], v[134:137], v[226:229], v[12:15]
	v_mfma_f32_16x16x32_bf16 v[8:11], v[142:145], v[226:229], v[8:11]
	s_setprio 0
	s_setprio 1
	v_mfma_f32_16x16x32_bf16 v[52:55], v[146:149], v[172:175], v[52:55]
	v_mfma_f32_16x16x32_bf16 v[48:51], v[164:167], v[172:175], v[48:51]
	v_mfma_f32_16x16x32_bf16 v[36:39], v[146:149], v[188:191], v[36:39]
	v_mfma_f32_16x16x32_bf16 v[32:35], v[164:167], v[188:191], v[32:35]
	v_mfma_f32_16x16x32_bf16 v[20:23], v[146:149], v[196:199], v[20:23]
	v_mfma_f32_16x16x32_bf16 v[16:19], v[164:167], v[196:199], v[16:19]
	v_mfma_f32_16x16x32_bf16 v[4:7], v[146:149], v[204:207], v[4:7]
	v_mfma_f32_16x16x32_bf16 v[0:3], v[164:167], v[204:207], v[0:3]
	v_mfma_f32_16x16x32_bf16 v[52:55], v[160:163], v[184:187], v[52:55]
	v_mfma_f32_16x16x32_bf16 v[48:51], v[168:171], v[184:187], v[48:51]
	v_mfma_f32_16x16x32_bf16 v[36:39], v[160:163], v[192:195], v[36:39]
	v_mfma_f32_16x16x32_bf16 v[32:35], v[168:171], v[192:195], v[32:35]
	v_mfma_f32_16x16x32_bf16 v[20:23], v[160:163], v[200:203], v[20:23]
	v_mfma_f32_16x16x32_bf16 v[16:19], v[168:171], v[200:203], v[16:19]
	v_mfma_f32_16x16x32_bf16 v[4:7], v[160:163], v[226:229], v[4:7]
	v_mfma_f32_16x16x32_bf16 v[0:3], v[168:171], v[226:229], v[0:3]
	s_setprio 0
	s_barrier
	s_add_i32 s11, s11, 2
	s_add_u32 s0, s0, 0x100
	s_addc_u32 s1, s1, 0
	s_add_u32 s9, s9, 0x100
	s_addc_u32 s10, s10, 0
	s_cmp_gt_u32 s11, 13
	s_cbranch_scc0 .LBB0_29
	s_and_b64 vcc, exec, s[22:23]
	s_cbranch_vccz .LBB0_32
	s_barrier
